# wait-state padding restored after the f32->bf16 peephole (static hazard check over the whole file)
# speedup vs baseline: 1.0047x; 1.0047x over previous
.LBB0_193:
	v_add_u32_e32 v14, 0x400, v162
	ds_write2_b32 v162, v64, v68 offset1:16
	ds_write2_b32 v162, v65, v69 offset0:128 offset1:144
	ds_write2_b32 v14, v66, v70 offset1:16
	ds_write2_b32 v14, v67, v71 offset0:128 offset1:144
	ds_write2_b32 v162, v72, v76 offset0:32 offset1:48
	ds_write2_b32 v162, v73, v77 offset0:160 offset1:176
	ds_write2_b32 v14, v74, v78 offset0:32 offset1:48
	ds_write2_b32 v14, v75, v79 offset0:160 offset1:176
	ds_write2_b32 v162, v80, v84 offset0:64 offset1:80
	ds_write2_b32 v162, v81, v85 offset0:192 offset1:208
	ds_write2_b32 v14, v82, v86 offset0:64 offset1:80
	ds_write2_b32 v14, v83, v87 offset0:192 offset1:208
	ds_write2st64_b32 v163, v88, v89 offset1:2
	ds_write2st64_b32 v163, v90, v91 offset0:4 offset1:6
	ds_write2st64_b32 v164, v92, v93 offset1:2
	ds_write2st64_b32 v164, v94, v95 offset0:4 offset1:6
	ds_read_b128 v[0:3], v161 offset:16
	ds_read_b128 v[4:7], v161
	s_waitcnt lgkmcnt(0)
	v_cvt_pk_bf16_f32 v3, v2, v3
	v_cvt_pk_bf16_f32 v2, v0, v1
	v_cvt_pk_bf16_f32 v1, v6, v7
	v_cvt_pk_bf16_f32 v0, v4, v5
	ds_read_b128 v[4:7], v166
	ds_read_b128 v[8:11], v166 offset:16
	v_mul_hi_u32_u24_e32 v13, s0, v165
	v_mul_u32_u24_e32 v12, s0, v165
	v_lshl_add_u64 v[12:13], v[12:13], 1, s[4:5]
	v_lshl_add_u64 v[12:13], v[12:13], 0, v[142:143]
	global_store_dwordx4 v[12:13], v[0:3], off
	s_waitcnt lgkmcnt(0)
	s_nop 0
	v_cvt_pk_bf16_f32 v3, v10, v11
	v_cvt_pk_bf16_f32 v2, v8, v9
	v_cvt_pk_bf16_f32 v1, v6, v7
	v_cvt_pk_bf16_f32 v0, v4, v5
	ds_read_b128 v[4:7], v168
	ds_read_b128 v[8:11], v168 offset:16
	v_mul_hi_u32_u24_e32 v13, s0, v167
	v_mul_u32_u24_e32 v12, s0, v167
	v_lshl_add_u64 v[12:13], v[12:13], 1, s[4:5]
	v_lshl_add_u64 v[12:13], v[12:13], 0, v[142:143]
	global_store_dwordx4 v[12:13], v[0:3], off
	s_waitcnt lgkmcnt(0)
	s_nop 0
	v_cvt_pk_bf16_f32 v3, v10, v11
	v_cvt_pk_bf16_f32 v2, v8, v9
	v_cvt_pk_bf16_f32 v1, v6, v7
	v_cvt_pk_bf16_f32 v0, v4, v5
	ds_read_b128 v[4:7], v170
	ds_read_b128 v[8:11], v170 offset:16
	v_mul_hi_u32_u24_e32 v13, s0, v169
	v_mul_u32_u24_e32 v12, s0, v169
	v_lshl_add_u64 v[12:13], v[12:13], 1, s[4:5]
	v_lshl_add_u64 v[12:13], v[12:13], 0, v[142:143]
	global_store_dwordx4 v[12:13], v[0:3], off
	s_waitcnt lgkmcnt(0)
	s_nop 0
	v_cvt_pk_bf16_f32 v3, v10, v11
	v_cvt_pk_bf16_f32 v0, v4, v5
	v_mul_hi_u32_u24_e32 v5, s0, v171
	v_mul_u32_u24_e32 v4, s0, v171
	v_lshl_add_u64 v[4:5], v[4:5], 1, s[4:5]
	v_cvt_pk_bf16_f32 v2, v8, v9
	v_cvt_pk_bf16_f32 v1, v6, v7
	v_lshl_add_u64 v[4:5], v[4:5], 0, v[142:143]
	global_store_dwordx4 v[4:5], v[0:3], off
	ds_write2_b32 v162, v96, v100 offset1:16
	ds_write2_b32 v162, v97, v101 offset0:128 offset1:144
	ds_write2_b32 v14, v98, v102 offset1:16
	ds_write2_b32 v14, v99, v103 offset0:128 offset1:144
	ds_write2_b32 v162, v104, v108 offset0:32 offset1:48
	ds_write2_b32 v162, v105, v109 offset0:160 offset1:176
	ds_write2_b32 v14, v106, v110 offset0:32 offset1:48
	ds_write2_b32 v14, v107, v111 offset0:160 offset1:176
	ds_write2_b32 v162, v112, v116 offset0:64 offset1:80
	ds_write2_b32 v162, v113, v117 offset0:192 offset1:208
	ds_write2_b32 v14, v114, v118 offset0:64 offset1:80
	ds_write2_b32 v14, v115, v119 offset0:192 offset1:208
	ds_write2st64_b32 v163, v120, v121 offset1:2
	ds_write2st64_b32 v163, v122, v123 offset0:4 offset1:6
	ds_write2st64_b32 v164, v124, v125 offset1:2
	ds_write2st64_b32 v164, v126, v127 offset0:4 offset1:6
	ds_read_b128 v[0:3], v161 offset:16
	ds_read_b128 v[4:7], v161
	s_waitcnt lgkmcnt(0)
	v_cvt_pk_bf16_f32 v3, v2, v3
	v_cvt_pk_bf16_f32 v2, v0, v1
	v_cvt_pk_bf16_f32 v1, v6, v7
	v_cvt_pk_bf16_f32 v0, v4, v5
	ds_read_b128 v[4:7], v166
	ds_read_b128 v[8:11], v166 offset:16
	v_mul_hi_u32_u24_e32 v13, s0, v172
	v_mul_u32_u24_e32 v12, s0, v172
	v_lshl_add_u64 v[12:13], v[12:13], 1, s[4:5]
	v_lshl_add_u64 v[12:13], v[12:13], 0, v[142:143]
	global_store_dwordx4 v[12:13], v[0:3], off
	s_waitcnt lgkmcnt(0)
	s_nop 0
	v_cvt_pk_bf16_f32 v3, v10, v11
	v_cvt_pk_bf16_f32 v2, v8, v9
	v_cvt_pk_bf16_f32 v1, v6, v7
	v_cvt_pk_bf16_f32 v0, v4, v5
	ds_read_b128 v[4:7], v168
	ds_read_b128 v[8:11], v168 offset:16
	v_mul_hi_u32_u24_e32 v13, s0, v173
	v_mul_u32_u24_e32 v12, s0, v173
	v_lshl_add_u64 v[12:13], v[12:13], 1, s[4:5]
	v_lshl_add_u64 v[12:13], v[12:13], 0, v[142:143]
	global_store_dwordx4 v[12:13], v[0:3], off
	s_waitcnt lgkmcnt(0)
	s_nop 0
	v_cvt_pk_bf16_f32 v3, v10, v11
	v_cvt_pk_bf16_f32 v2, v8, v9
	v_cvt_pk_bf16_f32 v1, v6, v7
	v_cvt_pk_bf16_f32 v0, v4, v5
	ds_read_b128 v[4:7], v170
	ds_read_b128 v[8:11], v170 offset:16
	v_mul_hi_u32_u24_e32 v13, s0, v174
	v_mul_u32_u24_e32 v12, s0, v174
	v_lshl_add_u64 v[12:13], v[12:13], 1, s[4:5]
	v_lshl_add_u64 v[12:13], v[12:13], 0, v[142:143]
	global_store_dwordx4 v[12:13], v[0:3], off
	s_waitcnt lgkmcnt(0)
	s_nop 0
	v_cvt_pk_bf16_f32 v3, v10, v11
	v_cvt_pk_bf16_f32 v0, v4, v5
	v_mul_hi_u32_u24_e32 v5, s0, v175
	v_mul_u32_u24_e32 v4, s0, v175
	v_lshl_add_u64 v[4:5], v[4:5], 1, s[4:5]
	v_cvt_pk_bf16_f32 v2, v8, v9
	v_cvt_pk_bf16_f32 v1, v6, v7
	v_lshl_add_u64 v[4:5], v[4:5], 0, v[142:143]
	global_store_dwordx4 v[4:5], v[0:3], off
	s_cbranch_execnz .LBB0_170

.LBB0_445:
	v_add_u32_e32 v14, 0x400, v164
	ds_write2_b32 v164, v76, v78 offset1:16
	ds_write2_b32 v164, v77, v79 offset0:128 offset1:144
	ds_write2_b32 v14, v88, v92 offset1:16
	ds_write2_b32 v14, v89, v93 offset0:128 offset1:144
	ds_write2_b32 v164, v80, v82 offset0:32 offset1:48
	ds_write2_b32 v164, v81, v83 offset0:160 offset1:176
	ds_write2_b32 v14, v96, v98 offset0:32 offset1:48
	ds_write2_b32 v14, v97, v99 offset0:160 offset1:176
	ds_write2_b32 v164, v84, v86 offset0:64 offset1:80
	ds_write2_b32 v164, v85, v87 offset0:192 offset1:208
	ds_write2_b32 v14, v100, v102 offset0:64 offset1:80
	ds_write2_b32 v14, v101, v103 offset0:192 offset1:208
	ds_write2st64_b32 v165, v90, v91 offset1:2
	ds_write2st64_b32 v165, v104, v105 offset0:4 offset1:6
	ds_write2st64_b32 v166, v94, v95 offset1:2
	ds_write2st64_b32 v166, v106, v107 offset0:4 offset1:6
	ds_read_b128 v[0:3], v163 offset:16
	ds_read_b128 v[4:7], v163
	s_waitcnt lgkmcnt(0)
	v_cvt_pk_bf16_f32 v3, v2, v3
	v_cvt_pk_bf16_f32 v2, v0, v1
	v_cvt_pk_bf16_f32 v0, v4, v5
	v_mul_u32_u24_e32 v4, s4, v167
	v_cvt_pk_bf16_f32 v1, v6, v7
	v_lshlrev_b32_e32 v12, 1, v4
	ds_read_b128 v[4:7], v168
	ds_read_b128 v[8:11], v168 offset:16
	v_mov_b32_e32 v13, v65
	v_lshl_add_u64 v[12:13], s[56:57], 0, v[12:13]
	v_lshl_add_u64 v[12:13], v[12:13], 0, v[64:65]
	global_store_dwordx4 v[12:13], v[0:3], off
	s_waitcnt lgkmcnt(0)
	s_nop 0
	v_cvt_pk_bf16_f32 v3, v10, v11
	v_cvt_pk_bf16_f32 v0, v4, v5
	v_mul_u32_u24_e32 v4, s4, v169
	v_cvt_pk_bf16_f32 v2, v8, v9
	v_cvt_pk_bf16_f32 v1, v6, v7
	v_lshlrev_b32_e32 v12, 1, v4
	ds_read_b128 v[4:7], v170
	ds_read_b128 v[8:11], v170 offset:16
	v_mov_b32_e32 v13, v65
	v_lshl_add_u64 v[12:13], s[56:57], 0, v[12:13]
	v_lshl_add_u64 v[12:13], v[12:13], 0, v[64:65]
	global_store_dwordx4 v[12:13], v[0:3], off
	s_waitcnt lgkmcnt(0)
	s_nop 0
	v_cvt_pk_bf16_f32 v3, v10, v11
	v_cvt_pk_bf16_f32 v0, v4, v5
	v_mul_u32_u24_e32 v4, s4, v171
	v_cvt_pk_bf16_f32 v2, v8, v9
	v_cvt_pk_bf16_f32 v1, v6, v7
	v_lshlrev_b32_e32 v12, 1, v4
	ds_read_b128 v[4:7], v172
	ds_read_b128 v[8:11], v172 offset:16
	v_mov_b32_e32 v13, v65
	v_lshl_add_u64 v[12:13], s[56:57], 0, v[12:13]
	v_lshl_add_u64 v[12:13], v[12:13], 0, v[64:65]
	global_store_dwordx4 v[12:13], v[0:3], off
	s_waitcnt lgkmcnt(0)
	s_nop 0
	v_cvt_pk_bf16_f32 v3, v10, v11
	v_cvt_pk_bf16_f32 v0, v4, v5
	v_mul_u32_u24_e32 v4, s4, v173
	v_lshlrev_b32_e32 v4, 1, v4
	v_mov_b32_e32 v5, v65
	v_lshl_add_u64 v[4:5], s[56:57], 0, v[4:5]
	v_cvt_pk_bf16_f32 v2, v8, v9
	v_cvt_pk_bf16_f32 v1, v6, v7
	v_lshl_add_u64 v[4:5], v[4:5], 0, v[64:65]
	global_store_dwordx4 v[4:5], v[0:3], off
	ds_write2_b32 v164, v108, v110 offset1:16
	ds_write2_b32 v164, v109, v111 offset0:128 offset1:144
	ds_write2_b32 v14, v120, v124 offset1:16
	ds_write2_b32 v14, v121, v125 offset0:128 offset1:144
	ds_write2_b32 v164, v112, v114 offset0:32 offset1:48
	ds_write2_b32 v164, v113, v115 offset0:160 offset1:176
	ds_write2_b32 v14, v140, v142 offset0:32 offset1:48
	ds_write2_b32 v14, v141, v143 offset0:160 offset1:176
	ds_write2_b32 v164, v116, v118 offset0:64 offset1:80
	ds_write2_b32 v164, v117, v119 offset0:192 offset1:208
	ds_write2_b32 v14, v144, v146 offset0:64 offset1:80
	ds_write2_b32 v14, v145, v147 offset0:192 offset1:208
	ds_write2st64_b32 v165, v122, v123 offset1:2
	ds_write2st64_b32 v165, v148, v149 offset0:4 offset1:6
	ds_write2st64_b32 v166, v126, v127 offset1:2
	ds_write2st64_b32 v166, v150, v151 offset0:4 offset1:6
	ds_read_b128 v[0:3], v163 offset:16
	ds_read_b128 v[4:7], v163
	s_waitcnt lgkmcnt(0)
	v_cvt_pk_bf16_f32 v3, v2, v3
	v_cvt_pk_bf16_f32 v2, v0, v1
	v_cvt_pk_bf16_f32 v0, v4, v5
	v_mul_u32_u24_e32 v4, s4, v174
	v_cvt_pk_bf16_f32 v1, v6, v7
	v_lshlrev_b32_e32 v12, 1, v4
	ds_read_b128 v[4:7], v168
	ds_read_b128 v[8:11], v168 offset:16
	v_mov_b32_e32 v13, v65
	v_lshl_add_u64 v[12:13], s[56:57], 0, v[12:13]
	v_lshl_add_u64 v[12:13], v[12:13], 0, v[64:65]
	global_store_dwordx4 v[12:13], v[0:3], off
	s_waitcnt lgkmcnt(0)
	s_nop 0
	v_cvt_pk_bf16_f32 v3, v10, v11
	v_cvt_pk_bf16_f32 v0, v4, v5
	v_mul_u32_u24_e32 v4, s4, v175
	v_cvt_pk_bf16_f32 v2, v8, v9
	v_cvt_pk_bf16_f32 v1, v6, v7
	v_lshlrev_b32_e32 v12, 1, v4
	ds_read_b128 v[4:7], v170
	ds_read_b128 v[8:11], v170 offset:16
	v_mov_b32_e32 v13, v65
	v_lshl_add_u64 v[12:13], s[56:57], 0, v[12:13]
	v_lshl_add_u64 v[12:13], v[12:13], 0, v[64:65]
	global_store_dwordx4 v[12:13], v[0:3], off
	s_waitcnt lgkmcnt(0)
	s_nop 0
	v_cvt_pk_bf16_f32 v3, v10, v11
	v_cvt_pk_bf16_f32 v0, v4, v5
	v_mul_u32_u24_e32 v4, s4, v176
	v_cvt_pk_bf16_f32 v2, v8, v9
	v_cvt_pk_bf16_f32 v1, v6, v7
	v_lshlrev_b32_e32 v12, 1, v4
	ds_read_b128 v[4:7], v172
	ds_read_b128 v[8:11], v172 offset:16
	v_mov_b32_e32 v13, v65
	v_lshl_add_u64 v[12:13], s[56:57], 0, v[12:13]
	v_lshl_add_u64 v[12:13], v[12:13], 0, v[64:65]
	global_store_dwordx4 v[12:13], v[0:3], off
	s_waitcnt lgkmcnt(0)
	s_nop 0
	v_cvt_pk_bf16_f32 v3, v10, v11
	v_cvt_pk_bf16_f32 v0, v4, v5
	v_mul_u32_u24_e32 v4, s4, v177
	v_lshlrev_b32_e32 v4, 1, v4
	v_mov_b32_e32 v5, v65
	v_lshl_add_u64 v[4:5], s[56:57], 0, v[4:5]
	v_cvt_pk_bf16_f32 v2, v8, v9
	v_cvt_pk_bf16_f32 v1, v6, v7
	v_lshl_add_u64 v[4:5], v[4:5], 0, v[64:65]
	global_store_dwordx4 v[4:5], v[0:3], off
	s_cbranch_execnz .LBB0_429

.LBB0_625:
	s_lshl_b64 s[56:57], s[56:57], 1
	v_readfirstlane_b32 s31, v129
	v_lshl_add_u64 v[98:99], v[60:61], 0, s[56:57]
	s_mov_b32 m0, s31
	v_readfirstlane_b32 s31, v162
	global_load_lds_dwordx4 v[98:99], off
	v_lshl_add_u64 v[100:101], v[98:99], 0, s[40:41]
	s_mov_b32 m0, s31
	v_readfirstlane_b32 s31, v163
	global_load_lds_dwordx4 v[100:101], off
	v_lshl_add_u64 v[100:101], v[98:99], 0, s[42:43]
	s_mov_b32 m0, s31
	v_readfirstlane_b32 s31, v164
	global_load_lds_dwordx4 v[100:101], off
	v_lshl_add_u64 v[98:99], v[98:99], 0, s[44:45]
	s_mov_b32 m0, s31
	v_readfirstlane_b32 s31, v165
	global_load_lds_dwordx4 v[98:99], off
	v_lshl_add_u64 v[98:99], v[92:93], 0, s[56:57]
	s_mov_b32 m0, s31
	v_readfirstlane_b32 s31, v166
	global_load_lds_dwordx4 v[98:99], off
	v_lshl_add_u64 v[100:101], v[98:99], 0, s[40:41]
	s_mov_b32 m0, s31
	v_readfirstlane_b32 s31, v167
	global_load_lds_dwordx4 v[100:101], off
	v_lshl_add_u64 v[100:101], v[98:99], 0, s[42:43]
	s_mov_b32 m0, s31
	v_readfirstlane_b32 s31, v168
	global_load_lds_dwordx4 v[100:101], off
	v_lshl_add_u64 v[98:99], v[98:99], 0, s[44:45]
	s_mov_b32 m0, s31
	s_mov_b64 s[56:57], 64
	global_load_lds_dwordx4 v[98:99], off
	s_waitcnt vmcnt(0)
	s_waitcnt vmcnt(0) lgkmcnt(0)
	s_barrier
	ds_read_b128 v[98:101], v169
	ds_read_b128 v[180:183], v170 offset:16384
	ds_read_b128 v[184:187], v170 offset:18432
	ds_read_b128 v[188:191], v170 offset:20480
	ds_read_b128 v[102:105], v169 offset:2048
	ds_read_b128 v[192:195], v170 offset:22528
	ds_read_b128 v[196:199], v170 offset:24576
	ds_read_b128 v[200:203], v170 offset:26624
	ds_read_b128 v[204:207], v170 offset:28672
	ds_read_b128 v[208:211], v170 offset:30720
	s_waitcnt lgkmcnt(8)
	v_mfma_f32_16x16x32_bf16 v[56:59], v[98:101], v[180:183], v[56:59]
	s_andn2_b64 vcc, exec, s[54:55]
	s_mov_b64 s[54:55], 0
	s_waitcnt lgkmcnt(7)
	v_mfma_f32_16x16x32_bf16 v[52:55], v[98:101], v[184:187], v[52:55]
	s_waitcnt lgkmcnt(6)
	v_mfma_f32_16x16x32_bf16 v[48:51], v[98:101], v[188:191], v[48:51]
	s_waitcnt lgkmcnt(4)
	v_mfma_f32_16x16x32_bf16 v[44:47], v[98:101], v[192:195], v[44:47]
	s_waitcnt lgkmcnt(3)
	v_mfma_f32_16x16x32_bf16 v[40:43], v[98:101], v[196:199], v[40:43]
	s_waitcnt lgkmcnt(2)
	v_mfma_f32_16x16x32_bf16 v[36:39], v[98:101], v[200:203], v[36:39]
	s_waitcnt lgkmcnt(1)
	v_mfma_f32_16x16x32_bf16 v[32:35], v[98:101], v[204:207], v[32:35]
	s_waitcnt lgkmcnt(0)
	v_mfma_f32_16x16x32_bf16 v[28:31], v[98:101], v[208:211], v[28:31]
	ds_read_b128 v[98:101], v171
	v_mfma_f32_16x16x32_bf16 v[24:27], v[102:105], v[184:187], v[24:27]
	v_mfma_f32_16x16x32_bf16 v[20:23], v[102:105], v[188:191], v[20:23]
	v_mfma_f32_16x16x32_bf16 v[16:19], v[102:105], v[192:195], v[16:19]
	v_mfma_f32_16x16x32_bf16 v[12:15], v[102:105], v[196:199], v[12:15]
	v_mfma_f32_16x16x32_bf16 v[8:11], v[102:105], v[200:203], v[8:11]
	v_mfma_f32_16x16x32_bf16 v[4:7], v[102:105], v[204:207], v[4:7]
	v_mfma_f32_16x16x32_bf16 v[0:3], v[102:105], v[208:211], v[0:3]
	ds_read_b128 v[102:105], v171 offset:2048
	ds_read_b128 v[180:183], v172 offset:16384
	ds_read_b128 v[184:187], v172 offset:18432
	ds_read_b128 v[188:191], v172 offset:20480
	ds_read_b128 v[192:195], v172 offset:22528
	ds_read_b128 v[196:199], v172 offset:24576
	ds_read_b128 v[200:203], v172 offset:26624
	ds_read_b128 v[204:207], v172 offset:28672
	ds_read_b128 v[208:211], v172 offset:30720
	s_waitcnt lgkmcnt(7)
	v_mfma_f32_16x16x32_bf16 v[56:59], v[98:101], v[180:183], v[56:59]
	s_waitcnt lgkmcnt(0)
	s_barrier
	v_mfma_f32_16x16x32_bf16 v[52:55], v[98:101], v[184:187], v[52:55]
	v_mfma_f32_16x16x32_bf16 v[48:51], v[98:101], v[188:191], v[48:51]
	v_mfma_f32_16x16x32_bf16 v[44:47], v[98:101], v[192:195], v[44:47]
	v_mfma_f32_16x16x32_bf16 v[40:43], v[98:101], v[196:199], v[40:43]
	v_mfma_f32_16x16x32_bf16 v[36:39], v[98:101], v[200:203], v[36:39]
	v_mfma_f32_16x16x32_bf16 v[32:35], v[98:101], v[204:207], v[32:35]
	v_mfma_f32_16x16x32_bf16 v[28:31], v[98:101], v[208:211], v[28:31]
	v_mfma_f32_16x16x32_bf16 v[24:27], v[102:105], v[184:187], v[24:27]
	v_mfma_f32_16x16x32_bf16 v[20:23], v[102:105], v[188:191], v[20:23]
	v_mfma_f32_16x16x32_bf16 v[16:19], v[102:105], v[192:195], v[16:19]
	v_mfma_f32_16x16x32_bf16 v[12:15], v[102:105], v[196:199], v[12:15]
	v_mfma_f32_16x16x32_bf16 v[8:11], v[102:105], v[200:203], v[8:11]
	v_mfma_f32_16x16x32_bf16 v[4:7], v[102:105], v[204:207], v[4:7]
	v_mfma_f32_16x16x32_bf16 v[0:3], v[102:105], v[208:211], v[0:3]
	s_cbranch_vccz .LBB0_625
	v_mul_f32_e32 v63, v63, v87
	v_mul_f32_e32 v63, v63, v91
	v_add_f32_e32 v87, v97, v63
	v_sub_f32_e32 v91, v87, v97
	v_sub_f32_e32 v63, v63, v91
	v_add_f32_e32 v63, v96, v63
	v_add_f32_e32 v91, v87, v63
	v_add_f32_e32 v60, v94, v95
	v_sub_f32_e32 v87, v91, v87
	v_sub_f32_e32 v63, v63, v87
	v_add_f32_e32 v87, v60, v91
	v_sub_f32_e32 v61, v60, v94
	v_sub_f32_e32 v94, v87, v60
	v_sub_f32_e32 v61, v95, v61
	v_sub_f32_e32 v95, v87, v94
	v_sub_f32_e32 v60, v60, v95
	v_sub_f32_e32 v91, v91, v94
	v_add_f32_e32 v60, v91, v60
	v_add_f32_e32 v91, v61, v63
	v_sub_f32_e32 v94, v91, v61
	v_sub_f32_e32 v95, v91, v94
	v_sub_f32_e32 v61, v61, v95
	v_sub_f32_e32 v63, v63, v94
	v_add_f32_e32 v60, v91, v60
	v_add_f32_e32 v61, v63, v61
	v_add_f32_e32 v63, v87, v60
	v_sub_f32_e32 v87, v63, v87
	v_sub_f32_e32 v60, v60, v87
	v_add_f32_e32 v60, v61, v60
	v_add_f32_e32 v60, v63, v60
	v_cmp_nlt_f32_e32 vcc, 1.0, v62
	s_mov_b32 s31, 0x33800000
	s_mov_b64 s[56:57], 0
	v_cndmask_b32_e32 v60, v173, v60, vcc
	v_cmp_neq_f32_e32 vcc, 1.0, v62
	s_nop 1
	v_cndmask_b32_e32 v60, v174, v60, vcc
	v_cmp_gt_f32_e32 vcc, s31, v62
	s_ashr_i32 s31, s30, 31
	s_lshl_b64 s[54:55], s[30:31], 15
	v_cndmask_b32_e64 v87, v60, -v62, vcc
	v_mul_f32_e32 v60, v87, v110
	v_mul_f32_e32 v60, 0x3fb8aa3b, v60
	v_mul_f32_e64 v61, v118, -v87
	v_mul_f32_e64 v63, v119, -v87
	v_mul_f32_e64 v91, v120, -v87
	v_exp_f32_e32 v176, v60
	v_mul_f32_e32 v61, 0x3fb8aa3b, v61
	v_mul_f32_e32 v63, 0x3fb8aa3b, v63
	v_mul_f32_e32 v91, 0x3fb8aa3b, v91
	v_exp_f32_e32 v61, v61
	v_exp_f32_e32 v63, v63
	v_exp_f32_e32 v180, v91
	v_mul_f32_e64 v91, v121, -v87
	v_mul_f32_e32 v91, 0x3fb8aa3b, v91
	v_exp_f32_e32 v181, v91
	v_lshl_add_u64 v[94:95], v[66:67], 0, s[54:55]
	v_mul_f32_e32 v56, v176, v56
	v_mul_f32_e32 v57, v176, v57
	v_readlane_b32 s54, v247, 13
	v_mul_f32_e32 v56, v61, v56
	v_mul_f32_e32 v57, v63, v57
	v_readlane_b32 s55, v247, 14
	v_mul_f32_e32 v60, v87, v111
	v_cndmask_b32_e64 v91, v56, 0, s[6:7]
	v_cndmask_b32_e64 v97, 0, v57, s[54:55]
	v_pk_mul_f32 v[56:57], v[176:177], v[58:59] op_sel_hi:[0,1]
	v_readlane_b32 s54, v247, 17
	v_mul_f32_e32 v60, 0x3fb8aa3b, v60
	v_pk_mul_f32 v[56:57], v[180:181], v[56:57]
	v_readlane_b32 s55, v247, 18
	v_exp_f32_e32 v104, v60
	s_nop 0
	v_cndmask_b32_e64 v56, v56, 0, s[54:55]
	v_readlane_b32 s54, v247, 15
	v_readlane_b32 s55, v247, 16
	v_bfe_u32 v101, v56, 16, 1
	s_nop 0
	v_cndmask_b32_e64 v57, v57, 0, s[54:55]
	v_bfe_u32 v99, v57, 16, 1
	v_add3_u32 v101, v56, v101, s47
	v_add3_u32 v57, v57, v99, s47
	v_mul_f32_e32 v52, v104, v52
	v_readlane_b32 s54, v247, 21
	v_cvt_pk_bf16_f32 v56, v91, v97
	v_perm_b32 v57, v57, v101, s33
	v_add_u32_e32 v58, v122, v108
	v_mul_f32_e32 v52, v61, v52
	v_readlane_b32 s55, v247, 22
	ds_write_b64 v58, v[56:57] offset:32768
	v_mul_f32_e32 v53, v104, v53
	v_cndmask_b32_e64 v56, v52, 0, s[54:55]
	v_readlane_b32 s54, v247, 19
	v_mul_f32_e32 v53, v63, v53
	v_readlane_b32 s55, v247, 20
	v_mul_f32_e32 v60, v87, v112
	v_mul_f32_e32 v60, 0x3fb8aa3b, v60
	v_cndmask_b32_e64 v57, 0, v53, s[54:55]
	v_pk_mul_f32 v[52:53], v[104:105], v[54:55] op_sel_hi:[0,1]
	v_readlane_b32 s54, v247, 25
	v_pk_mul_f32 v[52:53], v[180:181], v[52:53]
	v_readlane_b32 s55, v247, 26
	v_exp_f32_e32 v102, v60
	s_nop 0
	v_cndmask_b32_e64 v52, v52, 0, s[54:55]
	v_readlane_b32 s54, v247, 23
	v_readlane_b32 s55, v247, 24
	v_bfe_u32 v59, v52, 16, 1
	s_nop 0
	v_cndmask_b32_e64 v53, v53, 0, s[54:55]
	v_bfe_u32 v58, v53, 16, 1
	v_add3_u32 v59, v52, v59, s47
	v_add3_u32 v53, v53, v58, s47
	v_mul_f32_e32 v48, v102, v48
	v_readlane_b32 s54, v247, 29
	v_cvt_pk_bf16_f32 v52, v56, v57
	v_perm_b32 v53, v53, v59, s33
	v_add_u32_e32 v54, v122, v123
	v_mul_f32_e32 v48, v61, v48
	v_readlane_b32 s55, v247, 30
	ds_write_b64 v54, v[52:53] offset:32768
	v_mul_f32_e32 v49, v102, v49
	v_cndmask_b32_e64 v52, v48, 0, s[54:55]
	v_readlane_b32 s54, v247, 27
	v_mul_f32_e32 v49, v63, v49
	v_readlane_b32 s55, v247, 28
	v_mul_f32_e32 v60, v87, v113
	v_mul_f32_e32 v60, 0x3fb8aa3b, v60
	v_cndmask_b32_e64 v53, 0, v49, s[54:55]
	v_pk_mul_f32 v[48:49], v[102:103], v[50:51] op_sel_hi:[0,1]
	v_readlane_b32 s54, v247, 33
	v_pk_mul_f32 v[48:49], v[180:181], v[48:49]
	v_readlane_b32 s55, v247, 34
	v_exp_f32_e32 v100, v60
	s_nop 0
	v_cndmask_b32_e64 v48, v48, 0, s[54:55]
	v_readlane_b32 s54, v247, 31
	v_readlane_b32 s55, v247, 32
	v_bfe_u32 v55, v48, 16, 1
	s_nop 0
	v_cndmask_b32_e64 v49, v49, 0, s[54:55]
	v_bfe_u32 v54, v49, 16, 1
	v_add3_u32 v55, v48, v55, s47
	v_add3_u32 v49, v49, v54, s47
	v_mul_f32_e32 v44, v100, v44
	v_readlane_b32 s54, v247, 37
	v_cvt_pk_bf16_f32 v48, v52, v53
	v_perm_b32 v49, v49, v55, s33
	v_add_u32_e32 v50, v122, v124
	v_mul_f32_e32 v44, v61, v44
	v_readlane_b32 s55, v247, 38
	ds_write_b64 v50, v[48:49] offset:32768
	v_mul_f32_e32 v45, v100, v45
	v_cndmask_b32_e64 v48, v44, 0, s[54:55]
	v_readlane_b32 s54, v247, 35
	v_mul_f32_e32 v45, v63, v45
	v_readlane_b32 s55, v247, 36
	v_mul_f32_e32 v60, v87, v114
	v_mul_f32_e32 v60, 0x3fb8aa3b, v60
	v_cndmask_b32_e64 v49, 0, v45, s[54:55]
	v_pk_mul_f32 v[44:45], v[100:101], v[46:47] op_sel_hi:[0,1]
	v_readlane_b32 s54, v247, 41
	v_pk_mul_f32 v[44:45], v[180:181], v[44:45]
	v_readlane_b32 s55, v247, 42
	v_exp_f32_e32 v98, v60
	s_nop 0
	v_cndmask_b32_e64 v44, v44, 0, s[54:55]
	v_readlane_b32 s54, v247, 39
	v_readlane_b32 s55, v247, 40
	v_bfe_u32 v51, v44, 16, 1
	s_nop 0
	v_cndmask_b32_e64 v45, v45, 0, s[54:55]
	v_bfe_u32 v50, v45, 16, 1
	v_add3_u32 v51, v44, v51, s47
	v_add3_u32 v45, v45, v50, s47
	v_mul_f32_e32 v40, v98, v40
	v_readlane_b32 s54, v247, 45
	v_cvt_pk_bf16_f32 v44, v48, v49
	v_perm_b32 v45, v45, v51, s33
	v_add_u32_e32 v46, v122, v125
	v_mul_f32_e32 v40, v61, v40
	v_readlane_b32 s55, v247, 46
	ds_write_b64 v46, v[44:45] offset:32768
	v_mul_f32_e32 v41, v98, v41
	v_cndmask_b32_e64 v44, v40, 0, s[54:55]
	v_readlane_b32 s54, v247, 43
	v_mul_f32_e32 v41, v63, v41
	v_readlane_b32 s55, v247, 44
	v_mul_f32_e32 v60, v87, v115
	v_mul_f32_e32 v60, 0x3fb8aa3b, v60
	v_cndmask_b32_e64 v45, 0, v41, s[54:55]
	v_pk_mul_f32 v[40:41], v[98:99], v[42:43] op_sel_hi:[0,1]
	v_readlane_b32 s54, v247, 49
	v_pk_mul_f32 v[40:41], v[180:181], v[40:41]
	v_readlane_b32 s55, v247, 50
	v_exp_f32_e32 v96, v60
	s_nop 0
	v_cndmask_b32_e64 v40, v40, 0, s[54:55]
	v_readlane_b32 s54, v247, 47
	v_readlane_b32 s55, v247, 48
	v_bfe_u32 v47, v40, 16, 1
	s_nop 0
	v_cndmask_b32_e64 v41, v41, 0, s[54:55]
	v_bfe_u32 v46, v41, 16, 1
	v_add3_u32 v47, v40, v47, s47
	v_add3_u32 v41, v41, v46, s47
	v_mul_f32_e32 v36, v96, v36
	v_readlane_b32 s54, v247, 53
	v_cvt_pk_bf16_f32 v40, v44, v45
	v_perm_b32 v41, v41, v47, s33
	v_add_u32_e32 v42, v122, v126
	v_mul_f32_e32 v36, v61, v36
	v_readlane_b32 s55, v247, 54
	ds_write_b64 v42, v[40:41] offset:32768
	v_mul_f32_e32 v37, v96, v37
	v_cndmask_b32_e64 v40, v36, 0, s[54:55]
	v_readlane_b32 s54, v247, 51
	v_mul_f32_e32 v37, v63, v37
	v_readlane_b32 s55, v247, 52
	v_mul_f32_e32 v60, v87, v116
	v_mul_f32_e32 v60, 0x3fb8aa3b, v60
	v_cndmask_b32_e64 v41, 0, v37, s[54:55]
	v_pk_mul_f32 v[36:37], v[96:97], v[38:39] op_sel_hi:[0,1]
	v_readlane_b32 s54, v247, 57
	v_pk_mul_f32 v[36:37], v[180:181], v[36:37]
	v_readlane_b32 s55, v247, 58
	v_exp_f32_e32 v62, v60
	s_nop 0
	v_cndmask_b32_e64 v36, v36, 0, s[54:55]
	v_readlane_b32 s54, v247, 55
	v_readlane_b32 s55, v247, 56
	v_bfe_u32 v43, v36, 16, 1
	s_nop 0
	v_cndmask_b32_e64 v37, v37, 0, s[54:55]
	v_bfe_u32 v42, v37, 16, 1
	v_add3_u32 v43, v36, v43, s47
	v_add3_u32 v37, v37, v42, s47
	v_mul_f32_e32 v32, v62, v32
	v_readlane_b32 s54, v247, 61
	v_cvt_pk_bf16_f32 v36, v40, v41
	v_perm_b32 v37, v37, v43, s33
	v_add_u32_e32 v38, v122, v127
	v_mul_f32_e32 v32, v61, v32
	v_readlane_b32 s55, v247, 62
	v_mul_f32_e32 v60, v87, v117
	ds_write_b64 v38, v[36:37] offset:32768
	v_mul_f32_e32 v33, v62, v33
	v_cndmask_b32_e64 v36, v32, 0, s[54:55]
	v_readlane_b32 s54, v247, 59
	v_mul_f32_e32 v60, 0x3fb8aa3b, v60
	v_mul_f32_e32 v33, v63, v33
	v_readlane_b32 s55, v247, 60
	v_exp_f32_e32 v60, v60
	v_pk_mul_f32 v[24:25], v[104:105], v[24:25] op_sel_hi:[0,1]
	v_cndmask_b32_e64 v37, 0, v33, s[54:55]
	v_pk_mul_f32 v[32:33], v[62:63], v[34:35] op_sel_hi:[0,1]
	v_readlane_b32 s54, v247, 63
	v_pk_mul_f32 v[32:33], v[180:181], v[32:33]
	v_readlane_b32 s55, v246, 0
	v_cndmask_b32_e64 v32, v32, 0, s[60:61]
	s_nop 0
	v_cndmask_b32_e64 v33, v33, 0, s[54:55]
	v_bfe_u32 v38, v33, 16, 1
	v_bfe_u32 v39, v32, 16, 1
	v_add3_u32 v39, v32, v39, s47
	v_add3_u32 v33, v33, v38, s47
	v_mul_f32_e32 v28, v60, v28
	v_mul_f32_e32 v29, v60, v29
	v_cvt_pk_bf16_f32 v32, v36, v37
	v_perm_b32 v33, v33, v39, s33
	v_add_u32_e32 v34, v122, v140
	v_mul_f32_e32 v28, v61, v28
	v_mul_f32_e32 v29, v63, v29
	ds_write_b64 v34, v[32:33] offset:32768
	v_cndmask_b32_e64 v32, v28, 0, s[64:65]
	v_cndmask_b32_e64 v33, 0, v29, s[62:63]
	v_pk_mul_f32 v[28:29], v[60:61], v[30:31] op_sel_hi:[0,1]
	v_pk_mul_f32 v[28:29], v[180:181], v[28:29]
	v_cndmask_b32_e64 v28, v28, 0, s[68:69]
	v_cndmask_b32_e64 v29, v29, 0, s[66:67]
	v_bfe_u32 v34, v29, 16, 1
	v_bfe_u32 v35, v28, 16, 1
	v_add3_u32 v35, v28, v35, s47
	v_add3_u32 v29, v29, v34, s47
	v_cvt_pk_bf16_f32 v28, v32, v33
	v_perm_b32 v29, v29, v35, s33
	v_add_u32_e32 v30, v122, v141
	ds_write_b64 v30, v[28:29] offset:32768
	v_mul_f32_e64 v28, v142, -v87
	v_mul_f32_e64 v29, v143, -v87
	v_mul_f32_e32 v28, 0x3fb8aa3b, v28
	v_mul_f32_e32 v29, 0x3fb8aa3b, v29
	v_exp_f32_e32 v28, v28
	v_exp_f32_e32 v29, v29
	v_mul_f32_e64 v30, v144, -v87
	v_mul_f32_e64 v31, v145, -v87
	v_mul_f32_e32 v30, 0x3fb8aa3b, v30
	v_mul_f32_e32 v31, 0x3fb8aa3b, v31
	v_exp_f32_e32 v30, v30
	v_exp_f32_e32 v31, v31
	v_add_u32_e32 v32, v146, v108
	v_pk_mul_f32 v[24:25], v[28:29], v[24:25]
	ds_write_b64 v32, v[178:179] offset:32768
	v_cndmask_b32_e64 v32, v24, 0, s[6:7]
	v_cndmask_b32_e64 v33, v25, 0, s[70:71]
	v_pk_mul_f32 v[24:25], v[104:105], v[26:27] op_sel_hi:[0,1]
	v_pk_mul_f32 v[24:25], v[30:31], v[24:25]
	v_cndmask_b32_e64 v24, v24, 0, s[74:75]
	v_cndmask_b32_e64 v25, v25, 0, s[72:73]
	v_pk_mul_f32 v[20:21], v[102:103], v[20:21] op_sel_hi:[0,1]
	v_cvt_pk_bf16_f32 v25, v24, v25
	v_cvt_pk_bf16_f32 v24, v32, v33
	v_add_u32_e32 v26, v146, v123
	v_pk_mul_f32 v[20:21], v[28:29], v[20:21]
	ds_write_b64 v26, v[24:25] offset:32768
	v_cndmask_b32_e64 v24, v20, 0, s[78:79]
	v_cndmask_b32_e64 v25, v21, 0, s[76:77]
	v_pk_mul_f32 v[20:21], v[102:103], v[22:23] op_sel_hi:[0,1]
	v_pk_mul_f32 v[20:21], v[30:31], v[20:21]
	v_cndmask_b32_e64 v20, v20, 0, s[82:83]
	v_cndmask_b32_e64 v21, v21, 0, s[80:81]
	v_pk_mul_f32 v[16:17], v[100:101], v[16:17] op_sel_hi:[0,1]
	v_cvt_pk_bf16_f32 v21, v20, v21
	v_cvt_pk_bf16_f32 v20, v24, v25
	v_add_u32_e32 v22, v146, v124
	v_pk_mul_f32 v[16:17], v[28:29], v[16:17]
	ds_write_b64 v22, v[20:21] offset:32768
	v_cndmask_b32_e64 v20, v16, 0, s[86:87]
	v_cndmask_b32_e64 v21, v17, 0, s[84:85]
	v_pk_mul_f32 v[16:17], v[100:101], v[18:19] op_sel_hi:[0,1]
	v_pk_mul_f32 v[16:17], v[30:31], v[16:17]
	v_cndmask_b32_e64 v16, v16, 0, s[90:91]
	v_cndmask_b32_e64 v17, v17, 0, s[88:89]
	v_pk_mul_f32 v[12:13], v[98:99], v[12:13] op_sel_hi:[0,1]
	v_cvt_pk_bf16_f32 v17, v16, v17
	v_cvt_pk_bf16_f32 v16, v20, v21
	v_add_u32_e32 v18, v146, v125
	v_pk_mul_f32 v[12:13], v[28:29], v[12:13]
	ds_write_b64 v18, v[16:17] offset:32768
	v_cndmask_b32_e64 v16, v12, 0, s[94:95]
	v_cndmask_b32_e64 v17, v13, 0, s[92:93]
	v_pk_mul_f32 v[12:13], v[98:99], v[14:15] op_sel_hi:[0,1]
	v_pk_mul_f32 v[12:13], v[30:31], v[12:13]
	v_cndmask_b32_e64 v12, v12, 0, s[0:1]
	v_cndmask_b32_e64 v13, v13, 0, s[96:97]
	v_pk_mul_f32 v[8:9], v[96:97], v[8:9] op_sel_hi:[0,1]
	v_cvt_pk_bf16_f32 v13, v12, v13
	v_cvt_pk_bf16_f32 v12, v16, v17
	v_add_u32_e32 v14, v146, v126
	v_pk_mul_f32 v[8:9], v[28:29], v[8:9]
	ds_write_b64 v14, v[12:13] offset:32768
	v_cndmask_b32_e64 v12, v8, 0, s[4:5]
	v_cndmask_b32_e64 v13, v9, 0, s[28:29]
	v_pk_mul_f32 v[8:9], v[96:97], v[10:11] op_sel_hi:[0,1]
	v_pk_mul_f32 v[8:9], v[30:31], v[8:9]
	v_cndmask_b32_e64 v8, v8, 0, s[10:11]
	v_cndmask_b32_e64 v9, v9, 0, s[8:9]
	v_pk_mul_f32 v[4:5], v[62:63], v[4:5] op_sel_hi:[0,1]
	v_cvt_pk_bf16_f32 v9, v8, v9
	v_cvt_pk_bf16_f32 v8, v12, v13
	v_add_u32_e32 v10, v146, v127
	v_pk_mul_f32 v[4:5], v[28:29], v[4:5]
	ds_write_b64 v10, v[8:9] offset:32768
	v_cndmask_b32_e64 v8, v4, 0, s[14:15]
	v_cndmask_b32_e64 v9, v5, 0, s[12:13]
	v_pk_mul_f32 v[4:5], v[62:63], v[6:7] op_sel_hi:[0,1]
	v_pk_mul_f32 v[4:5], v[30:31], v[4:5]
	v_cndmask_b32_e64 v4, v4, 0, s[18:19]
	v_cndmask_b32_e64 v5, v5, 0, s[16:17]
	v_pk_mul_f32 v[0:1], v[60:61], v[0:1] op_sel_hi:[0,1]
	v_cvt_pk_bf16_f32 v5, v4, v5
	v_cvt_pk_bf16_f32 v4, v8, v9
	v_add_u32_e32 v6, v146, v140
	v_pk_mul_f32 v[0:1], v[28:29], v[0:1]
	ds_write_b64 v6, v[4:5] offset:32768
	v_cndmask_b32_e64 v4, v0, 0, s[22:23]
	v_cndmask_b32_e64 v5, v1, 0, s[20:21]
	v_pk_mul_f32 v[0:1], v[60:61], v[2:3] op_sel_hi:[0,1]
	v_pk_mul_f32 v[0:1], v[30:31], v[0:1]
	v_cndmask_b32_e64 v0, v0, 0, s[26:27]
	v_cndmask_b32_e64 v1, v1, 0, s[24:25]
	v_cvt_pk_bf16_f32 v1, v0, v1
	v_cvt_pk_bf16_f32 v0, v4, v5
	v_add_u32_e32 v2, v146, v141
	v_mov_b32_e32 v32, 0
	ds_write_b64 v2, v[0:1] offset:32768
	v_mov_b32_e32 v33, v32
	v_mov_b32_e32 v34, v32
	v_mov_b32_e32 v35, v32
	v_mov_b32_e32 v36, v32
	v_mov_b32_e32 v37, v32
	v_mov_b32_e32 v38, v32
	v_mov_b32_e32 v39, v32
	v_mov_b32_e32 v40, v32
	v_mov_b32_e32 v41, v32
	v_mov_b32_e32 v42, v32
	v_mov_b32_e32 v43, v32
	v_mov_b32_e32 v44, v32
	v_mov_b32_e32 v45, v32
	v_mov_b32_e32 v46, v32
	v_mov_b32_e32 v47, v32
	v_mov_b32_e32 v48, v32
	v_mov_b32_e32 v49, v32
	v_mov_b32_e32 v50, v32
	v_mov_b32_e32 v51, v32
	v_mov_b32_e32 v52, v32
	v_mov_b32_e32 v53, v32
	v_mov_b32_e32 v54, v32
	v_mov_b32_e32 v55, v32
	v_mov_b32_e32 v56, v32
	v_mov_b32_e32 v57, v32
	v_mov_b32_e32 v58, v32
	v_mov_b32_e32 v59, v32
	v_mov_b32_e32 v60, v32
	v_mov_b32_e32 v61, v32
	v_mov_b32_e32 v62, v32
	v_mov_b32_e32 v63, v32
	v_mov_b32_e32 v0, v32
	v_mov_b32_e32 v1, v32
	v_mov_b32_e32 v2, v32
	v_mov_b32_e32 v3, v32
	v_mov_b32_e32 v8, v32
	v_mov_b32_e32 v9, v32
	v_mov_b32_e32 v10, v32
	v_mov_b32_e32 v11, v32
	v_mov_b32_e32 v12, v32
	v_mov_b32_e32 v13, v32
	v_mov_b32_e32 v14, v32
	v_mov_b32_e32 v15, v32
	v_mov_b32_e32 v16, v32
	v_mov_b32_e32 v17, v32
	v_mov_b32_e32 v18, v32
	v_mov_b32_e32 v19, v32
	v_mov_b32_e32 v20, v32
	v_mov_b32_e32 v21, v32
	v_mov_b32_e32 v22, v32
	v_mov_b32_e32 v23, v32
	v_mov_b32_e32 v24, v32
	v_mov_b32_e32 v25, v32
	v_mov_b32_e32 v26, v32
	v_mov_b32_e32 v27, v32
	v_mov_b32_e32 v28, v32
	v_mov_b32_e32 v29, v32
	v_mov_b32_e32 v30, v32
	v_mov_b32_e32 v31, v32
	v_mov_b32_e32 v4, v32
	v_mov_b32_e32 v5, v32
	v_mov_b32_e32 v6, v32
	v_mov_b32_e32 v7, v32
	s_mov_b64 s[54:55], -1
